# dense-attn unrolled loop: 4 LDS waits per step instead of 8, m0 writes hoisted over their pad nops
# baseline (speedup 1.0000x reference)
.Lattn6:
	ds_read_b64_tr_b16 v[204:205], v199 offset:24576
	ds_read_b64_tr_b16 v[206:207], v199 offset:25088
	v_add_f32_e32 v220, v64, v220
	v_add_f32_e32 v221, v65, v221
	v_add_f32_e32 v222, v66, v222
	v_add_f32_e32 v223, v67, v223
	v_add_f32_e32 v220, v68, v220
	v_add_f32_e32 v221, v69, v221
	v_cvt_pk_bf16_f32 v154, v64, v65
	v_cvt_pk_bf16_f32 v155, v66, v67
	v_mfma_f32_32x32x16_bf16 v[96:111], v[80:83], v[158:161], v[32:47]
	ds_read_b64_tr_b16 v[64:65], v199 offset:28672
	ds_read_b64_tr_b16 v[66:67], v199 offset:29184
	v_add_f32_e32 v222, v70, v222
	v_add_f32_e32 v223, v71, v223
	v_add_f32_e32 v220, v72, v220
	v_add_f32_e32 v221, v73, v221
	v_mfma_f32_32x32x16_bf16 v[80:95], v[166:169], v[158:161], v[32:47]
	v_cvt_pk_bf16_f32 v156, v68, v69
	v_cvt_pk_bf16_f32 v157, v70, v71
	ds_read_b64_tr_b16 v[68:69], v199 offset:25600
	ds_read_b64_tr_b16 v[70:71], v199 offset:26112
	v_add_f32_e32 v222, v74, v222
	v_add_f32_e32 v223, v75, v223
	v_add_f32_e32 v220, v76, v220
	v_add_f32_e32 v221, v77, v221
	v_cvt_pk_bf16_f32 v146, v72, v73
	v_cvt_pk_bf16_f32 v147, v74, v75
	v_mfma_f32_32x32x16_bf16 v[96:111], v[170:173], v[150:153], v[96:111]
	ds_read_b64_tr_b16 v[72:73], v199 offset:29696
	ds_read_b64_tr_b16 v[74:75], v199 offset:30208
	v_mfma_f32_32x32x16_bf16 v[80:95], v[162:165], v[150:153], v[80:95]
	v_add_f32_e32 v222, v78, v222
	v_add_f32_e32 v223, v79, v223
	v_add_f32_e32 v220, v48, v220
	v_add_f32_e32 v221, v49, v221
	v_cvt_pk_bf16_f32 v148, v76, v77
	v_cvt_pk_bf16_f32 v149, v78, v79
	ds_read_b64_tr_b16 v[76:77], v199 offset:26624
	ds_read_b64_tr_b16 v[78:79], v199 offset:27136
	v_mfma_f32_32x32x16_bf16 v[96:111], v[124:127], v[142:145], v[96:111]
	v_add_f32_e32 v222, v50, v222
	v_add_f32_e32 v223, v51, v223
	v_add_f32_e32 v220, v52, v220
	v_add_f32_e32 v221, v53, v221
	v_cvt_pk_bf16_f32 v138, v48, v49
	v_cvt_pk_bf16_f32 v139, v50, v51
	ds_read_b64_tr_b16 v[48:49], v199 offset:30720
	ds_read_b64_tr_b16 v[50:51], v199 offset:31232
	v_mfma_f32_32x32x16_bf16 v[80:95], v[120:123], v[142:145], v[80:95]
	v_add_f32_e32 v222, v54, v222
	v_add_f32_e32 v223, v55, v223
	v_add_f32_e32 v220, v56, v220
	v_add_f32_e32 v221, v57, v221
	v_cvt_pk_bf16_f32 v140, v52, v53
	v_cvt_pk_bf16_f32 v141, v54, v55
	ds_read_b64_tr_b16 v[52:53], v199 offset:27648
	ds_read_b64_tr_b16 v[54:55], v199 offset:28160
	v_mfma_f32_32x32x16_bf16 v[96:111], v[116:119], v[134:137], v[96:111]
	v_add_f32_e32 v222, v58, v222
	v_add_f32_e32 v223, v59, v223
	v_add_f32_e32 v220, v60, v220
	v_add_f32_e32 v221, v61, v221
	v_cvt_pk_bf16_f32 v130, v56, v57
	v_cvt_pk_bf16_f32 v131, v58, v59
	ds_read_b64_tr_b16 v[56:57], v199 offset:31744
	ds_read_b64_tr_b16 v[58:59], v199 offset:32256
	v_mfma_f32_32x32x16_bf16 v[80:95], v[112:115], v[134:137], v[80:95]
	v_add_f32_e32 v222, v62, v222
	v_add_f32_e32 v223, v63, v223
	v_cvt_pk_bf16_f32 v132, v60, v61
	s_add_i32 m0, s5, 0x2000
	v_cvt_pk_bf16_f32 v133, v62, v63
	global_load_lds_dwordx4 v216, s[98:99]
	s_add_i32 m0, s4, 0x4000
	s_nop 0
	global_load_lds_dwordx4 v217, s[100:101]
	s_waitcnt lgkmcnt(12)
	v_mfma_f32_32x32x16_bf16 v[0:15], v[154:157], v[204:207], v[0:15]
	v_exp_f32_e32 v96, v96
	v_exp_f32_e32 v97, v97
	v_exp_f32_e32 v98, v98
	v_exp_f32_e32 v99, v99
	v_mfma_f32_32x32x16_bf16 v[16:31], v[154:157], v[64:67], v[16:31]
	v_exp_f32_e32 v100, v100
	v_exp_f32_e32 v101, v101
	v_exp_f32_e32 v102, v102
	v_exp_f32_e32 v103, v103
	ds_read_b128 v[60:63], v200 offset:16384
	ds_read_b128 v[116:119], v200 offset:16896
	s_waitcnt lgkmcnt(10)
	v_mfma_f32_32x32x16_bf16 v[0:15], v[146:149], v[68:71], v[0:15]
	v_exp_f32_e32 v104, v104
	v_exp_f32_e32 v105, v105
	v_exp_f32_e32 v106, v106
	v_exp_f32_e32 v107, v107
	ds_read_b128 v[120:123], v200 offset:18432
	ds_read_b128 v[124:127], v200 offset:18944
	v_mfma_f32_32x32x16_bf16 v[16:31], v[146:149], v[72:75], v[16:31]
	v_exp_f32_e32 v108, v108
	v_exp_f32_e32 v109, v109
	v_exp_f32_e32 v110, v110
	v_exp_f32_e32 v111, v111
	ds_read_b128 v[162:165], v200 offset:20480
	ds_read_b128 v[166:169], v200 offset:20992
	s_waitcnt lgkmcnt(10)
	v_mfma_f32_32x32x16_bf16 v[0:15], v[138:141], v[76:79], v[0:15]
	v_exp_f32_e32 v80, v80
	v_exp_f32_e32 v81, v81
	v_exp_f32_e32 v82, v82
	v_exp_f32_e32 v83, v83
	ds_read_b128 v[170:173], v200 offset:22528
	ds_read_b128 v[112:115], v200 offset:23040
	v_mfma_f32_32x32x16_bf16 v[16:31], v[138:141], v[48:51], v[16:31]
	v_exp_f32_e32 v84, v84
	v_exp_f32_e32 v85, v85
	v_exp_f32_e32 v86, v86
	v_exp_f32_e32 v87, v87
	s_waitcnt lgkmcnt(8)
	v_mfma_f32_32x32x16_bf16 v[0:15], v[130:133], v[52:55], v[0:15]
	v_exp_f32_e32 v88, v88
	v_exp_f32_e32 v89, v89
	v_exp_f32_e32 v90, v90
	v_exp_f32_e32 v91, v91
	v_mfma_f32_32x32x16_bf16 v[16:31], v[130:133], v[56:59], v[16:31]
	v_exp_f32_e32 v92, v92
	v_exp_f32_e32 v93, v93
	v_exp_f32_e32 v94, v94
	v_exp_f32_e32 v95, v95
	s_waitcnt vmcnt(2) lgkmcnt(0)
	s_barrier
	ds_read_b64_tr_b16 v[204:205], v199 offset:32768
	ds_read_b64_tr_b16 v[206:207], v199 offset:33280
	v_mfma_f32_32x32x16_bf16 v[64:79], v[60:63], v[158:161], v[32:47]
	v_add_f32_e32 v220, v96, v220
	v_add_f32_e32 v221, v97, v221
	v_add_f32_e32 v222, v98, v222
	v_add_f32_e32 v223, v99, v223
	v_add_f32_e32 v220, v100, v220
	v_add_f32_e32 v221, v101, v221
	v_cvt_pk_bf16_f32 v154, v96, v97
	v_cvt_pk_bf16_f32 v155, v98, v99
	ds_read_b64_tr_b16 v[96:97], v199 offset:36864
	ds_read_b64_tr_b16 v[98:99], v199 offset:37376
	v_add_f32_e32 v222, v102, v222
	v_add_f32_e32 v223, v103, v223
	v_add_f32_e32 v220, v104, v220
	v_add_f32_e32 v221, v105, v221
	v_mfma_f32_32x32x16_bf16 v[48:63], v[116:119], v[158:161], v[32:47]
	v_cvt_pk_bf16_f32 v156, v100, v101
	v_cvt_pk_bf16_f32 v157, v102, v103
	ds_read_b64_tr_b16 v[100:101], v199 offset:33792
	ds_read_b64_tr_b16 v[102:103], v199 offset:34304
	v_mfma_f32_32x32x16_bf16 v[64:79], v[120:123], v[150:153], v[64:79]
	v_add_f32_e32 v222, v106, v222
	v_add_f32_e32 v223, v107, v223
	v_add_f32_e32 v220, v108, v220
	v_add_f32_e32 v221, v109, v221
	v_cvt_pk_bf16_f32 v146, v104, v105
	v_cvt_pk_bf16_f32 v147, v106, v107
	ds_read_b64_tr_b16 v[104:105], v199 offset:37888
	ds_read_b64_tr_b16 v[106:107], v199 offset:38400
	v_mfma_f32_32x32x16_bf16 v[48:63], v[124:127], v[150:153], v[48:63]
	v_add_f32_e32 v222, v110, v222
	v_add_f32_e32 v223, v111, v223
	v_add_f32_e32 v220, v80, v220
	v_add_f32_e32 v221, v81, v221
	v_cvt_pk_bf16_f32 v148, v108, v109
	v_cvt_pk_bf16_f32 v149, v110, v111
	ds_read_b64_tr_b16 v[108:109], v199 offset:34816
	ds_read_b64_tr_b16 v[110:111], v199 offset:35328
	v_mfma_f32_32x32x16_bf16 v[64:79], v[162:165], v[142:145], v[64:79]
	v_add_f32_e32 v222, v82, v222
	v_add_f32_e32 v223, v83, v223
	v_add_f32_e32 v220, v84, v220
	v_add_f32_e32 v221, v85, v221
	v_cvt_pk_bf16_f32 v138, v80, v81
	v_cvt_pk_bf16_f32 v139, v82, v83
	ds_read_b64_tr_b16 v[208:209], v199 offset:38912
	ds_read_b64_tr_b16 v[210:211], v199 offset:39424
	v_mfma_f32_32x32x16_bf16 v[48:63], v[166:169], v[142:145], v[48:63]
	v_add_f32_e32 v222, v86, v222
	v_add_f32_e32 v223, v87, v223
	v_add_f32_e32 v220, v88, v220
	v_add_f32_e32 v221, v89, v221
	v_cvt_pk_bf16_f32 v140, v84, v85
	v_cvt_pk_bf16_f32 v141, v86, v87
	ds_read_b64_tr_b16 v[84:85], v199 offset:35840
	ds_read_b64_tr_b16 v[86:87], v199 offset:36352
	v_mfma_f32_32x32x16_bf16 v[64:79], v[170:173], v[134:137], v[64:79]
	v_add_f32_e32 v222, v90, v222
	v_add_f32_e32 v223, v91, v223
	v_add_f32_e32 v220, v92, v220
	v_add_f32_e32 v221, v93, v221
	v_cvt_pk_bf16_f32 v130, v88, v89
	v_cvt_pk_bf16_f32 v131, v90, v91
	ds_read_b64_tr_b16 v[88:89], v199 offset:39936
	ds_read_b64_tr_b16 v[90:91], v199 offset:40448
	v_mfma_f32_32x32x16_bf16 v[48:63], v[112:115], v[134:137], v[48:63]
	v_add_f32_e32 v222, v94, v222
	v_add_f32_e32 v223, v95, v223
	v_cvt_pk_bf16_f32 v132, v92, v93
	s_add_i32 m0, s5, 0x4000
	v_cvt_pk_bf16_f32 v133, v94, v95
	global_load_lds_dwordx4 v218, s[98:99]
	s_mov_b32 m0, s4
	s_nop 0
	global_load_lds_dwordx4 v219, s[100:101]
	s_waitcnt lgkmcnt(12)
	v_mfma_f32_32x32x16_bf16 v[0:15], v[154:157], v[204:207], v[0:15]
	v_exp_f32_e32 v64, v64
	v_exp_f32_e32 v65, v65
	v_exp_f32_e32 v66, v66
	v_exp_f32_e32 v67, v67
	v_mfma_f32_32x32x16_bf16 v[16:31], v[154:157], v[96:99], v[16:31]
	v_exp_f32_e32 v68, v68
	v_exp_f32_e32 v69, v69
	v_exp_f32_e32 v70, v70
	v_exp_f32_e32 v71, v71
	ds_read_b128 v[80:83], v200
	ds_read_b128 v[166:169], v200 offset:512
	s_waitcnt lgkmcnt(10)
	v_mfma_f32_32x32x16_bf16 v[0:15], v[146:149], v[100:103], v[0:15]
	v_exp_f32_e32 v72, v72
	v_exp_f32_e32 v73, v73
	v_exp_f32_e32 v74, v74
	v_exp_f32_e32 v75, v75
	ds_read_b128 v[170:173], v200 offset:2048
	ds_read_b128 v[162:165], v200 offset:2560
	v_mfma_f32_32x32x16_bf16 v[16:31], v[146:149], v[104:107], v[16:31]
	v_exp_f32_e32 v76, v76
	v_exp_f32_e32 v77, v77
	v_exp_f32_e32 v78, v78
	v_exp_f32_e32 v79, v79
	ds_read_b128 v[124:127], v200 offset:4096
	ds_read_b128 v[120:123], v200 offset:4608
	s_waitcnt lgkmcnt(10)
	v_mfma_f32_32x32x16_bf16 v[0:15], v[138:141], v[108:111], v[0:15]
	v_exp_f32_e32 v48, v48
	v_exp_f32_e32 v49, v49
	v_exp_f32_e32 v50, v50
	v_exp_f32_e32 v51, v51
	ds_read_b128 v[116:119], v200 offset:6144
	ds_read_b128 v[112:115], v200 offset:6656
	v_mfma_f32_32x32x16_bf16 v[16:31], v[138:141], v[208:211], v[16:31]
	v_exp_f32_e32 v52, v52
	v_exp_f32_e32 v53, v53
	v_exp_f32_e32 v54, v54
	v_exp_f32_e32 v55, v55
	s_waitcnt lgkmcnt(8)
	v_mfma_f32_32x32x16_bf16 v[0:15], v[130:133], v[84:87], v[0:15]
	v_exp_f32_e32 v56, v56
	v_exp_f32_e32 v57, v57
	v_exp_f32_e32 v58, v58
	v_exp_f32_e32 v59, v59
	v_mfma_f32_32x32x16_bf16 v[16:31], v[130:133], v[88:91], v[16:31]
	v_exp_f32_e32 v60, v60
	v_exp_f32_e32 v61, v61
	v_exp_f32_e32 v62, v62
	v_exp_f32_e32 v63, v63
	s_waitcnt vmcnt(2) lgkmcnt(0)
	s_barrier
	s_add_u32 s98, s98, 0x8000
	s_addc_u32 s99, s99, 0
	s_add_u32 s100, s100, 0x8000
	s_addc_u32 s101, s101, 0
	ds_read_b64_tr_b16 v[204:205], v199 offset:40960
	ds_read_b64_tr_b16 v[206:207], v199 offset:41472
	v_add_f32_e32 v220, v64, v220
	v_add_f32_e32 v221, v65, v221
	v_add_f32_e32 v222, v66, v222
	v_add_f32_e32 v223, v67, v223
	v_add_f32_e32 v220, v68, v220
	v_add_f32_e32 v221, v69, v221
	v_cvt_pk_bf16_f32 v154, v64, v65
	v_cvt_pk_bf16_f32 v155, v66, v67
	v_mfma_f32_32x32x16_bf16 v[96:111], v[80:83], v[158:161], v[32:47]
	ds_read_b64_tr_b16 v[64:65], v199 offset:45056
	ds_read_b64_tr_b16 v[66:67], v199 offset:45568
	v_add_f32_e32 v222, v70, v222
	v_add_f32_e32 v223, v71, v223
	v_add_f32_e32 v220, v72, v220
	v_add_f32_e32 v221, v73, v221
	v_mfma_f32_32x32x16_bf16 v[80:95], v[166:169], v[158:161], v[32:47]
	v_cvt_pk_bf16_f32 v156, v68, v69
	v_cvt_pk_bf16_f32 v157, v70, v71
	ds_read_b64_tr_b16 v[68:69], v199 offset:41984
	ds_read_b64_tr_b16 v[70:71], v199 offset:42496
	v_add_f32_e32 v222, v74, v222
	v_add_f32_e32 v223, v75, v223
	v_add_f32_e32 v220, v76, v220
	v_add_f32_e32 v221, v77, v221
	v_cvt_pk_bf16_f32 v146, v72, v73
	v_cvt_pk_bf16_f32 v147, v74, v75
	v_mfma_f32_32x32x16_bf16 v[96:111], v[170:173], v[150:153], v[96:111]
	ds_read_b64_tr_b16 v[72:73], v199 offset:46080
	ds_read_b64_tr_b16 v[74:75], v199 offset:46592
	v_mfma_f32_32x32x16_bf16 v[80:95], v[162:165], v[150:153], v[80:95]
	v_add_f32_e32 v222, v78, v222
	v_add_f32_e32 v223, v79, v223
	v_add_f32_e32 v220, v48, v220
	v_add_f32_e32 v221, v49, v221
	v_cvt_pk_bf16_f32 v148, v76, v77
	v_cvt_pk_bf16_f32 v149, v78, v79
	ds_read_b64_tr_b16 v[76:77], v199 offset:43008
	ds_read_b64_tr_b16 v[78:79], v199 offset:43520
	v_mfma_f32_32x32x16_bf16 v[96:111], v[124:127], v[142:145], v[96:111]
	v_add_f32_e32 v222, v50, v222
	v_add_f32_e32 v223, v51, v223
	v_add_f32_e32 v220, v52, v220
	v_add_f32_e32 v221, v53, v221
	v_cvt_pk_bf16_f32 v138, v48, v49
	v_cvt_pk_bf16_f32 v139, v50, v51
	ds_read_b64_tr_b16 v[48:49], v199 offset:47104
	ds_read_b64_tr_b16 v[50:51], v199 offset:47616
	v_mfma_f32_32x32x16_bf16 v[80:95], v[120:123], v[142:145], v[80:95]
	v_add_f32_e32 v222, v54, v222
	v_add_f32_e32 v223, v55, v223
	v_add_f32_e32 v220, v56, v220
	v_add_f32_e32 v221, v57, v221
	v_cvt_pk_bf16_f32 v140, v52, v53
	v_cvt_pk_bf16_f32 v141, v54, v55
	ds_read_b64_tr_b16 v[52:53], v199 offset:44032
	ds_read_b64_tr_b16 v[54:55], v199 offset:44544
	v_mfma_f32_32x32x16_bf16 v[96:111], v[116:119], v[134:137], v[96:111]
	v_add_f32_e32 v222, v58, v222
	v_add_f32_e32 v223, v59, v223
	v_add_f32_e32 v220, v60, v220
	v_add_f32_e32 v221, v61, v221
	v_cvt_pk_bf16_f32 v130, v56, v57
	v_cvt_pk_bf16_f32 v131, v58, v59
	ds_read_b64_tr_b16 v[56:57], v199 offset:48128
	ds_read_b64_tr_b16 v[58:59], v199 offset:48640
	v_mfma_f32_32x32x16_bf16 v[80:95], v[112:115], v[134:137], v[80:95]
	v_add_f32_e32 v222, v62, v222
	v_add_f32_e32 v223, v63, v223
	v_cvt_pk_bf16_f32 v132, v60, v61
	s_mov_b32 m0, s5
	v_cvt_pk_bf16_f32 v133, v62, v63
	global_load_lds_dwordx4 v216, s[98:99]
	s_add_i32 m0, s4, 0x2000
	s_nop 0
	global_load_lds_dwordx4 v217, s[100:101]
	s_waitcnt lgkmcnt(12)
	v_mfma_f32_32x32x16_bf16 v[0:15], v[154:157], v[204:207], v[0:15]
	v_exp_f32_e32 v96, v96
	v_exp_f32_e32 v97, v97
	v_exp_f32_e32 v98, v98
	v_exp_f32_e32 v99, v99
	v_mfma_f32_32x32x16_bf16 v[16:31], v[154:157], v[64:67], v[16:31]
	v_exp_f32_e32 v100, v100
	v_exp_f32_e32 v101, v101
	v_exp_f32_e32 v102, v102
	v_exp_f32_e32 v103, v103
	ds_read_b128 v[60:63], v200 offset:8192
	ds_read_b128 v[116:119], v200 offset:8704
	s_waitcnt lgkmcnt(10)
	v_mfma_f32_32x32x16_bf16 v[0:15], v[146:149], v[68:71], v[0:15]
	v_exp_f32_e32 v104, v104
	v_exp_f32_e32 v105, v105
	v_exp_f32_e32 v106, v106
	v_exp_f32_e32 v107, v107
	ds_read_b128 v[120:123], v200 offset:10240
	ds_read_b128 v[124:127], v200 offset:10752
	v_mfma_f32_32x32x16_bf16 v[16:31], v[146:149], v[72:75], v[16:31]
	v_exp_f32_e32 v108, v108
	v_exp_f32_e32 v109, v109
	v_exp_f32_e32 v110, v110
	v_exp_f32_e32 v111, v111
	ds_read_b128 v[162:165], v200 offset:12288
	ds_read_b128 v[166:169], v200 offset:12800
	s_waitcnt lgkmcnt(10)
	v_mfma_f32_32x32x16_bf16 v[0:15], v[138:141], v[76:79], v[0:15]
	v_exp_f32_e32 v80, v80
	v_exp_f32_e32 v81, v81
	v_exp_f32_e32 v82, v82
	v_exp_f32_e32 v83, v83
	ds_read_b128 v[170:173], v200 offset:14336
	ds_read_b128 v[112:115], v200 offset:14848
	v_mfma_f32_32x32x16_bf16 v[16:31], v[138:141], v[48:51], v[16:31]
	v_exp_f32_e32 v84, v84
	v_exp_f32_e32 v85, v85
	v_exp_f32_e32 v86, v86
	v_exp_f32_e32 v87, v87
	s_waitcnt lgkmcnt(8)
	v_mfma_f32_32x32x16_bf16 v[0:15], v[130:133], v[52:55], v[0:15]
	v_exp_f32_e32 v88, v88
	v_exp_f32_e32 v89, v89
	v_exp_f32_e32 v90, v90
	v_exp_f32_e32 v91, v91
	v_mfma_f32_32x32x16_bf16 v[16:31], v[130:133], v[56:59], v[16:31]
	v_exp_f32_e32 v92, v92
	v_exp_f32_e32 v93, v93
	v_exp_f32_e32 v94, v94
	v_exp_f32_e32 v95, v95
	s_waitcnt vmcnt(2) lgkmcnt(0)
	s_barrier
	ds_read_b64_tr_b16 v[204:205], v199 offset:24576
	ds_read_b64_tr_b16 v[206:207], v199 offset:25088
	v_mfma_f32_32x32x16_bf16 v[64:79], v[60:63], v[158:161], v[32:47]
	v_add_f32_e32 v220, v96, v220
	v_add_f32_e32 v221, v97, v221
	v_add_f32_e32 v222, v98, v222
	v_add_f32_e32 v223, v99, v223
	v_add_f32_e32 v220, v100, v220
	v_add_f32_e32 v221, v101, v221
	v_cvt_pk_bf16_f32 v154, v96, v97
	v_cvt_pk_bf16_f32 v155, v98, v99
	ds_read_b64_tr_b16 v[96:97], v199 offset:28672
	ds_read_b64_tr_b16 v[98:99], v199 offset:29184
	v_add_f32_e32 v222, v102, v222
	v_add_f32_e32 v223, v103, v223
	v_add_f32_e32 v220, v104, v220
	v_add_f32_e32 v221, v105, v221
	v_mfma_f32_32x32x16_bf16 v[48:63], v[116:119], v[158:161], v[32:47]
	v_cvt_pk_bf16_f32 v156, v100, v101
	v_cvt_pk_bf16_f32 v157, v102, v103
	ds_read_b64_tr_b16 v[100:101], v199 offset:25600
	ds_read_b64_tr_b16 v[102:103], v199 offset:26112
	v_mfma_f32_32x32x16_bf16 v[64:79], v[120:123], v[150:153], v[64:79]
	v_add_f32_e32 v222, v106, v222
	v_add_f32_e32 v223, v107, v223
	v_add_f32_e32 v220, v108, v220
	v_add_f32_e32 v221, v109, v221
	v_cvt_pk_bf16_f32 v146, v104, v105
	v_cvt_pk_bf16_f32 v147, v106, v107
	ds_read_b64_tr_b16 v[104:105], v199 offset:29696
	ds_read_b64_tr_b16 v[106:107], v199 offset:30208
	v_mfma_f32_32x32x16_bf16 v[48:63], v[124:127], v[150:153], v[48:63]
	v_add_f32_e32 v222, v110, v222
	v_add_f32_e32 v223, v111, v223
	v_add_f32_e32 v220, v80, v220
	v_add_f32_e32 v221, v81, v221
	v_cvt_pk_bf16_f32 v148, v108, v109
	v_cvt_pk_bf16_f32 v149, v110, v111
	ds_read_b64_tr_b16 v[108:109], v199 offset:26624
	ds_read_b64_tr_b16 v[110:111], v199 offset:27136
	v_mfma_f32_32x32x16_bf16 v[64:79], v[162:165], v[142:145], v[64:79]
	v_add_f32_e32 v222, v82, v222
	v_add_f32_e32 v223, v83, v223
	v_add_f32_e32 v220, v84, v220
	v_add_f32_e32 v221, v85, v221
	v_cvt_pk_bf16_f32 v138, v80, v81
	v_cvt_pk_bf16_f32 v139, v82, v83
	ds_read_b64_tr_b16 v[208:209], v199 offset:30720
	ds_read_b64_tr_b16 v[210:211], v199 offset:31232
	v_mfma_f32_32x32x16_bf16 v[48:63], v[166:169], v[142:145], v[48:63]
	v_add_f32_e32 v222, v86, v222
	v_add_f32_e32 v223, v87, v223
	v_add_f32_e32 v220, v88, v220
	v_add_f32_e32 v221, v89, v221
	v_cvt_pk_bf16_f32 v140, v84, v85
	v_cvt_pk_bf16_f32 v141, v86, v87
	ds_read_b64_tr_b16 v[84:85], v199 offset:27648
	ds_read_b64_tr_b16 v[86:87], v199 offset:28160
	v_mfma_f32_32x32x16_bf16 v[64:79], v[170:173], v[134:137], v[64:79]
	v_add_f32_e32 v222, v90, v222
	v_add_f32_e32 v223, v91, v223
	v_add_f32_e32 v220, v92, v220
	v_add_f32_e32 v221, v93, v221
	v_cvt_pk_bf16_f32 v130, v88, v89
	v_cvt_pk_bf16_f32 v131, v90, v91
	ds_read_b64_tr_b16 v[88:89], v199 offset:31744
	ds_read_b64_tr_b16 v[90:91], v199 offset:32256
	v_mfma_f32_32x32x16_bf16 v[48:63], v[112:115], v[134:137], v[48:63]
	v_add_f32_e32 v222, v94, v222
	v_add_f32_e32 v223, v95, v223
	v_cvt_pk_bf16_f32 v132, v92, v93
	s_add_i32 m0, s5, 0x2000
	v_cvt_pk_bf16_f32 v133, v94, v95
	global_load_lds_dwordx4 v218, s[98:99]
	s_add_i32 m0, s4, 0x4000
	s_nop 0
	global_load_lds_dwordx4 v219, s[100:101]
	s_waitcnt lgkmcnt(12)
	v_mfma_f32_32x32x16_bf16 v[0:15], v[154:157], v[204:207], v[0:15]
	v_exp_f32_e32 v64, v64
	v_exp_f32_e32 v65, v65
	v_exp_f32_e32 v66, v66
	v_exp_f32_e32 v67, v67
	v_mfma_f32_32x32x16_bf16 v[16:31], v[154:157], v[96:99], v[16:31]
	v_exp_f32_e32 v68, v68
	v_exp_f32_e32 v69, v69
	v_exp_f32_e32 v70, v70
	v_exp_f32_e32 v71, v71
	ds_read_b128 v[80:83], v200 offset:16384
	ds_read_b128 v[166:169], v200 offset:16896
	s_waitcnt lgkmcnt(10)
	v_mfma_f32_32x32x16_bf16 v[0:15], v[146:149], v[100:103], v[0:15]
	v_exp_f32_e32 v72, v72
	v_exp_f32_e32 v73, v73
	v_exp_f32_e32 v74, v74
	v_exp_f32_e32 v75, v75
	ds_read_b128 v[170:173], v200 offset:18432
	ds_read_b128 v[162:165], v200 offset:18944
	v_mfma_f32_32x32x16_bf16 v[16:31], v[146:149], v[104:107], v[16:31]
	v_exp_f32_e32 v76, v76
	v_exp_f32_e32 v77, v77
	v_exp_f32_e32 v78, v78
	v_exp_f32_e32 v79, v79
	ds_read_b128 v[124:127], v200 offset:20480
	ds_read_b128 v[120:123], v200 offset:20992
	s_waitcnt lgkmcnt(10)
	v_mfma_f32_32x32x16_bf16 v[0:15], v[138:141], v[108:111], v[0:15]
	v_exp_f32_e32 v48, v48
	v_exp_f32_e32 v49, v49
	v_exp_f32_e32 v50, v50
	v_exp_f32_e32 v51, v51
	ds_read_b128 v[116:119], v200 offset:22528
	ds_read_b128 v[112:115], v200 offset:23040
	v_mfma_f32_32x32x16_bf16 v[16:31], v[138:141], v[208:211], v[16:31]
	v_exp_f32_e32 v52, v52
	v_exp_f32_e32 v53, v53
	v_exp_f32_e32 v54, v54
	v_exp_f32_e32 v55, v55
	s_waitcnt lgkmcnt(8)
	v_mfma_f32_32x32x16_bf16 v[0:15], v[130:133], v[84:87], v[0:15]
	v_exp_f32_e32 v56, v56
	v_exp_f32_e32 v57, v57
	v_exp_f32_e32 v58, v58
	v_exp_f32_e32 v59, v59
	v_mfma_f32_32x32x16_bf16 v[16:31], v[130:133], v[88:91], v[16:31]
	v_exp_f32_e32 v60, v60
	v_exp_f32_e32 v61, v61
	v_exp_f32_e32 v62, v62
	v_exp_f32_e32 v63, v63
	s_waitcnt vmcnt(2) lgkmcnt(0)
	s_barrier
	s_add_u32 s98, s98, 0x8000
	s_addc_u32 s99, s99, 0
	s_add_u32 s100, s100, 0x8000
	s_addc_u32 s101, s101, 0
	ds_read_b64_tr_b16 v[204:205], v199 offset:32768
	ds_read_b64_tr_b16 v[206:207], v199 offset:33280
	v_add_f32_e32 v220, v64, v220
	v_add_f32_e32 v221, v65, v221
	v_add_f32_e32 v222, v66, v222
	v_add_f32_e32 v223, v67, v223
	v_add_f32_e32 v220, v68, v220
	v_add_f32_e32 v221, v69, v221
	v_cvt_pk_bf16_f32 v154, v64, v65
	v_cvt_pk_bf16_f32 v155, v66, v67
	v_mfma_f32_32x32x16_bf16 v[96:111], v[80:83], v[158:161], v[32:47]
	ds_read_b64_tr_b16 v[64:65], v199 offset:36864
	ds_read_b64_tr_b16 v[66:67], v199 offset:37376
	v_add_f32_e32 v222, v70, v222
	v_add_f32_e32 v223, v71, v223
	v_add_f32_e32 v220, v72, v220
	v_add_f32_e32 v221, v73, v221
	v_mfma_f32_32x32x16_bf16 v[80:95], v[166:169], v[158:161], v[32:47]
	v_cvt_pk_bf16_f32 v156, v68, v69
	v_cvt_pk_bf16_f32 v157, v70, v71
	ds_read_b64_tr_b16 v[68:69], v199 offset:33792
	ds_read_b64_tr_b16 v[70:71], v199 offset:34304
	v_add_f32_e32 v222, v74, v222
	v_add_f32_e32 v223, v75, v223
	v_add_f32_e32 v220, v76, v220
	v_add_f32_e32 v221, v77, v221
	v_cvt_pk_bf16_f32 v146, v72, v73
	v_cvt_pk_bf16_f32 v147, v74, v75
	v_mfma_f32_32x32x16_bf16 v[96:111], v[170:173], v[150:153], v[96:111]
	ds_read_b64_tr_b16 v[72:73], v199 offset:37888
	ds_read_b64_tr_b16 v[74:75], v199 offset:38400
	v_mfma_f32_32x32x16_bf16 v[80:95], v[162:165], v[150:153], v[80:95]
	v_add_f32_e32 v222, v78, v222
	v_add_f32_e32 v223, v79, v223
	v_add_f32_e32 v220, v48, v220
	v_add_f32_e32 v221, v49, v221
	v_cvt_pk_bf16_f32 v148, v76, v77
	v_cvt_pk_bf16_f32 v149, v78, v79
	ds_read_b64_tr_b16 v[76:77], v199 offset:34816
	ds_read_b64_tr_b16 v[78:79], v199 offset:35328
	v_mfma_f32_32x32x16_bf16 v[96:111], v[124:127], v[142:145], v[96:111]
	v_add_f32_e32 v222, v50, v222
	v_add_f32_e32 v223, v51, v223
	v_add_f32_e32 v220, v52, v220
	v_add_f32_e32 v221, v53, v221
	v_cvt_pk_bf16_f32 v138, v48, v49
	v_cvt_pk_bf16_f32 v139, v50, v51
	ds_read_b64_tr_b16 v[48:49], v199 offset:38912
	ds_read_b64_tr_b16 v[50:51], v199 offset:39424
	v_mfma_f32_32x32x16_bf16 v[80:95], v[120:123], v[142:145], v[80:95]
	v_add_f32_e32 v222, v54, v222
	v_add_f32_e32 v223, v55, v223
	v_add_f32_e32 v220, v56, v220
	v_add_f32_e32 v221, v57, v221
	v_cvt_pk_bf16_f32 v140, v52, v53
	v_cvt_pk_bf16_f32 v141, v54, v55
	ds_read_b64_tr_b16 v[52:53], v199 offset:35840
	ds_read_b64_tr_b16 v[54:55], v199 offset:36352
	v_mfma_f32_32x32x16_bf16 v[96:111], v[116:119], v[134:137], v[96:111]
	v_add_f32_e32 v222, v58, v222
	v_add_f32_e32 v223, v59, v223
	v_add_f32_e32 v220, v60, v220
	v_add_f32_e32 v221, v61, v221
	v_cvt_pk_bf16_f32 v130, v56, v57
	v_cvt_pk_bf16_f32 v131, v58, v59
	ds_read_b64_tr_b16 v[56:57], v199 offset:39936
	ds_read_b64_tr_b16 v[58:59], v199 offset:40448
	v_mfma_f32_32x32x16_bf16 v[80:95], v[112:115], v[134:137], v[80:95]
	v_add_f32_e32 v222, v62, v222
	v_add_f32_e32 v223, v63, v223
	v_cvt_pk_bf16_f32 v132, v60, v61
	s_add_i32 m0, s5, 0x4000
	v_cvt_pk_bf16_f32 v133, v62, v63
	global_load_lds_dwordx4 v216, s[98:99]
	s_mov_b32 m0, s4
	s_nop 0
	global_load_lds_dwordx4 v217, s[100:101]
	s_waitcnt lgkmcnt(12)
	v_mfma_f32_32x32x16_bf16 v[0:15], v[154:157], v[204:207], v[0:15]
	v_exp_f32_e32 v96, v96
	v_exp_f32_e32 v97, v97
	v_exp_f32_e32 v98, v98
	v_exp_f32_e32 v99, v99
	v_mfma_f32_32x32x16_bf16 v[16:31], v[154:157], v[64:67], v[16:31]
	v_exp_f32_e32 v100, v100
	v_exp_f32_e32 v101, v101
	v_exp_f32_e32 v102, v102
	v_exp_f32_e32 v103, v103
	ds_read_b128 v[60:63], v200
	ds_read_b128 v[116:119], v200 offset:512
	s_waitcnt lgkmcnt(10)
	v_mfma_f32_32x32x16_bf16 v[0:15], v[146:149], v[68:71], v[0:15]
	v_exp_f32_e32 v104, v104
	v_exp_f32_e32 v105, v105
	v_exp_f32_e32 v106, v106
	v_exp_f32_e32 v107, v107
	ds_read_b128 v[120:123], v200 offset:2048
	ds_read_b128 v[124:127], v200 offset:2560
	v_mfma_f32_32x32x16_bf16 v[16:31], v[146:149], v[72:75], v[16:31]
	v_exp_f32_e32 v108, v108
	v_exp_f32_e32 v109, v109
	v_exp_f32_e32 v110, v110
	v_exp_f32_e32 v111, v111
	ds_read_b128 v[162:165], v200 offset:4096
	ds_read_b128 v[166:169], v200 offset:4608
	s_waitcnt lgkmcnt(10)
	v_mfma_f32_32x32x16_bf16 v[0:15], v[138:141], v[76:79], v[0:15]
	v_exp_f32_e32 v80, v80
	v_exp_f32_e32 v81, v81
	v_exp_f32_e32 v82, v82
	v_exp_f32_e32 v83, v83
	ds_read_b128 v[170:173], v200 offset:6144
	ds_read_b128 v[112:115], v200 offset:6656
	v_mfma_f32_32x32x16_bf16 v[16:31], v[138:141], v[48:51], v[16:31]
	v_exp_f32_e32 v84, v84
	v_exp_f32_e32 v85, v85
	v_exp_f32_e32 v86, v86
	v_exp_f32_e32 v87, v87
	s_waitcnt lgkmcnt(8)
	v_mfma_f32_32x32x16_bf16 v[0:15], v[130:133], v[52:55], v[0:15]
	v_exp_f32_e32 v88, v88
	v_exp_f32_e32 v89, v89
	v_exp_f32_e32 v90, v90
	v_exp_f32_e32 v91, v91
	v_mfma_f32_32x32x16_bf16 v[16:31], v[130:133], v[56:59], v[16:31]
	v_exp_f32_e32 v92, v92
	v_exp_f32_e32 v93, v93
	v_exp_f32_e32 v94, v94
	v_exp_f32_e32 v95, v95
	s_waitcnt vmcnt(2) lgkmcnt(0)
	s_barrier
; #define WAIT_BAR(N) asm volatile("s_waitcnt vmcnt(" #N ") lgkmcnt(0)\n\ts_barrier":::"memory")
;   #define RESC() do{}while(0)
;   #define ROT() do{sl_prev=sl_cur;sl_cur=sl_next;sl_next=(sl_next==(NSLOT-1)*SLOTB)?0:sl_next+SLOTB;}while(0)
; template<int THRL> __device__ __forceinline__ void attn_unit(int b,int h,int qb,const bf16*Q,const bf16*__restrict__ K,const bf16*__restrict__ V,bf16*O,float*gssrow,float mref,char*shm){
;     ...
;   for(;t+5<NT;t+=2){
;     STEP(pB0,pB1,pA0,pA1,t,true,true,true);     WAIT_BAR(2); RESC(); ROT();
;     STEP(pA0,pA1,pB0,pB1,t+1,true,true,true);   WAIT_BAR(2); RESC(); ROT();
;   }
	ds_read_b64_tr_b16 v[204:205], v199 offset:40960
	ds_read_b64_tr_b16 v[206:207], v199 offset:41472
	v_mfma_f32_32x32x16_bf16 v[64:79], v[60:63], v[158:161], v[32:47]
	v_add_f32_e32 v220, v96, v220
	v_add_f32_e32 v221, v97, v221
	v_add_f32_e32 v222, v98, v222
	v_add_f32_e32 v223, v99, v223
	v_add_f32_e32 v220, v100, v220
	v_add_f32_e32 v221, v101, v221
	v_cvt_pk_bf16_f32 v154, v96, v97
	v_cvt_pk_bf16_f32 v155, v98, v99
	ds_read_b64_tr_b16 v[96:97], v199 offset:45056
	ds_read_b64_tr_b16 v[98:99], v199 offset:45568
	v_add_f32_e32 v222, v102, v222
	v_add_f32_e32 v223, v103, v223
	v_add_f32_e32 v220, v104, v220
	v_add_f32_e32 v221, v105, v221
	v_mfma_f32_32x32x16_bf16 v[48:63], v[116:119], v[158:161], v[32:47]
	v_cvt_pk_bf16_f32 v156, v100, v101
	v_cvt_pk_bf16_f32 v157, v102, v103
	ds_read_b64_tr_b16 v[100:101], v199 offset:41984
	ds_read_b64_tr_b16 v[102:103], v199 offset:42496
	v_mfma_f32_32x32x16_bf16 v[64:79], v[120:123], v[150:153], v[64:79]
	v_add_f32_e32 v222, v106, v222
	v_add_f32_e32 v223, v107, v223
	v_add_f32_e32 v220, v108, v220
	v_add_f32_e32 v221, v109, v221
	v_cvt_pk_bf16_f32 v146, v104, v105
	v_cvt_pk_bf16_f32 v147, v106, v107
	ds_read_b64_tr_b16 v[104:105], v199 offset:46080
	ds_read_b64_tr_b16 v[106:107], v199 offset:46592
	v_mfma_f32_32x32x16_bf16 v[48:63], v[124:127], v[150:153], v[48:63]
	v_add_f32_e32 v222, v110, v222
	v_add_f32_e32 v223, v111, v223
	v_add_f32_e32 v220, v80, v220
	v_add_f32_e32 v221, v81, v221
	v_cvt_pk_bf16_f32 v148, v108, v109
	v_cvt_pk_bf16_f32 v149, v110, v111
	ds_read_b64_tr_b16 v[108:109], v199 offset:43008
	ds_read_b64_tr_b16 v[110:111], v199 offset:43520
	v_mfma_f32_32x32x16_bf16 v[64:79], v[162:165], v[142:145], v[64:79]
	v_add_f32_e32 v222, v82, v222
	v_add_f32_e32 v223, v83, v223
	v_add_f32_e32 v220, v84, v220
	v_add_f32_e32 v221, v85, v221
	v_cvt_pk_bf16_f32 v138, v80, v81
	v_cvt_pk_bf16_f32 v139, v82, v83
	ds_read_b64_tr_b16 v[208:209], v199 offset:47104
	ds_read_b64_tr_b16 v[210:211], v199 offset:47616
	v_mfma_f32_32x32x16_bf16 v[48:63], v[166:169], v[142:145], v[48:63]
	v_add_f32_e32 v222, v86, v222
	v_add_f32_e32 v223, v87, v223
	v_add_f32_e32 v220, v88, v220
	v_add_f32_e32 v221, v89, v221
	v_cvt_pk_bf16_f32 v140, v84, v85
	v_cvt_pk_bf16_f32 v141, v86, v87
	ds_read_b64_tr_b16 v[84:85], v199 offset:44032
	ds_read_b64_tr_b16 v[86:87], v199 offset:44544
	v_mfma_f32_32x32x16_bf16 v[64:79], v[170:173], v[134:137], v[64:79]
	v_add_f32_e32 v222, v90, v222
	v_add_f32_e32 v223, v91, v223
	v_add_f32_e32 v220, v92, v220
	v_add_f32_e32 v221, v93, v221
	v_cvt_pk_bf16_f32 v130, v88, v89
	v_cvt_pk_bf16_f32 v131, v90, v91
	ds_read_b64_tr_b16 v[88:89], v199 offset:48128
	ds_read_b64_tr_b16 v[90:91], v199 offset:48640
	v_mfma_f32_32x32x16_bf16 v[48:63], v[112:115], v[134:137], v[48:63]
	v_add_f32_e32 v222, v94, v222
	v_add_f32_e32 v223, v95, v223
	v_cvt_pk_bf16_f32 v132, v92, v93
	s_mov_b32 m0, s5
	v_cvt_pk_bf16_f32 v133, v94, v95
	global_load_lds_dwordx4 v218, s[98:99]
	s_add_i32 m0, s4, 0x2000
	s_nop 0
	global_load_lds_dwordx4 v219, s[100:101]
	s_waitcnt lgkmcnt(12)
	v_mfma_f32_32x32x16_bf16 v[0:15], v[154:157], v[204:207], v[0:15]
	v_exp_f32_e32 v64, v64
	v_exp_f32_e32 v65, v65
	v_exp_f32_e32 v66, v66
	v_exp_f32_e32 v67, v67
	v_mfma_f32_32x32x16_bf16 v[16:31], v[154:157], v[96:99], v[16:31]
	v_exp_f32_e32 v68, v68
	v_exp_f32_e32 v69, v69
	v_exp_f32_e32 v70, v70
	v_exp_f32_e32 v71, v71
	ds_read_b128 v[80:83], v200 offset:8192
	ds_read_b128 v[166:169], v200 offset:8704
	s_waitcnt lgkmcnt(10)
	v_mfma_f32_32x32x16_bf16 v[0:15], v[146:149], v[100:103], v[0:15]
	v_exp_f32_e32 v72, v72
	v_exp_f32_e32 v73, v73
	v_exp_f32_e32 v74, v74
	v_exp_f32_e32 v75, v75
	ds_read_b128 v[170:173], v200 offset:10240
	ds_read_b128 v[162:165], v200 offset:10752
	v_mfma_f32_32x32x16_bf16 v[16:31], v[146:149], v[104:107], v[16:31]
	v_exp_f32_e32 v76, v76
	v_exp_f32_e32 v77, v77
	v_exp_f32_e32 v78, v78
	v_exp_f32_e32 v79, v79
	ds_read_b128 v[124:127], v200 offset:12288
	ds_read_b128 v[120:123], v200 offset:12800
	s_waitcnt lgkmcnt(10)
	v_mfma_f32_32x32x16_bf16 v[0:15], v[138:141], v[108:111], v[0:15]
	v_exp_f32_e32 v48, v48
	v_exp_f32_e32 v49, v49
	v_exp_f32_e32 v50, v50
	v_exp_f32_e32 v51, v51
	ds_read_b128 v[116:119], v200 offset:14336
	ds_read_b128 v[112:115], v200 offset:14848
	v_mfma_f32_32x32x16_bf16 v[16:31], v[138:141], v[208:211], v[16:31]
	v_exp_f32_e32 v52, v52
	v_exp_f32_e32 v53, v53
	v_exp_f32_e32 v54, v54
	v_exp_f32_e32 v55, v55
	s_waitcnt lgkmcnt(8)
	v_mfma_f32_32x32x16_bf16 v[0:15], v[130:133], v[84:87], v[0:15]
	v_exp_f32_e32 v56, v56
	v_exp_f32_e32 v57, v57
	v_exp_f32_e32 v58, v58
	v_exp_f32_e32 v59, v59
	v_mfma_f32_32x32x16_bf16 v[16:31], v[130:133], v[88:91], v[16:31]
	v_exp_f32_e32 v60, v60
	v_exp_f32_e32 v61, v61
	v_exp_f32_e32 v62, v62
	v_exp_f32_e32 v63, v63
	s_waitcnt vmcnt(2) lgkmcnt(0)
	s_barrier
	s_add_u32 s98, s98, 0x8000
	s_addc_u32 s99, s99, 0
	s_add_u32 s100, s100, 0x8000
	s_addc_u32 s101, s101, 0
	s_add_i32 s20, s20, 6
	s_cmpk_lg_i32 s20, 0xf5
	s_cbranch_scc1 .Lattn6
	v_add_f32_e32 v220, v220, v221
	v_add_f32_e32 v222, v222, v223
	v_add_f32_e32 v220, v220, v222
	v_add_f32_e32 v203, v203, v220
